# same x4 param-load hoist applied to rowop kind1 second norm, rowop kind0 second block, prep-L0 loop; KF 4 serialized loads batched
# speedup vs baseline: 1.0168x; 1.0010x over previous
.LBB0_34:
	v_cmp_gt_i32_e32 vcc, 0, v40
	v_min_i32_e32 v0, 0x4000, v26
	v_mov_b32_e32 v2, s23
	v_mov_b32_e32 v3, s89
	v_ashrrev_i32_e32 v31, 13, v0
	v_cndmask_b32_e32 v1, 0, v27, vcc
	v_cndmask_b32_e32 v0, v40, v26, vcc
	v_cndmask_b32_e32 v3, v2, v3, vcc
	v_mov_b32_e32 v2, s22
	v_mov_b32_e32 v4, s88
	v_cndmask_b32_e32 v2, v2, v4, vcc
	v_lshlrev_b64 v[0:1], 12, v[0:1]
	v_lshl_add_u64 v[0:1], v[2:3], 0, v[0:1]
	v_lshl_add_u64 v[36:37], v[0:1], 0, v[192:193]
	global_load_dwordx4 v[12:15], v[36:37], off nt
	global_load_dwordx4 v[8:11], v[36:37], off offset:1024 nt
	global_load_dwordx4 v[4:7], v[36:37], off offset:2048 nt
	global_load_dwordx4 v[0:3], v[36:37], off offset:3072 nt
	global_load_dwordx2 v[56:57], v[28:29], off
	global_load_dwordx2 v[64:65], v[28:29], off offset:512
	global_load_dwordx2 v[72:73], v[28:29], off offset:1024
	global_load_dwordx2 v[80:81], v[28:29], off offset:1536
	v_mul_hi_i32_i24_e32 v39, 0x6000, v31
	v_mul_i32_i24_e32 v38, 0x6000, v31
	v_lshl_add_u64 v[38:39], s[90:91], 0, v[38:39]
	s_waitcnt vmcnt(11)
	v_lshl_add_u64 v[52:53], v[38:39], 0, v[192:193]
	v_lshl_add_u64 v[76:77], v[52:53], 0, s[34:35]
	v_add_co_u32_e32 v52, vcc, s24, v52
	global_load_dwordx4 v[48:51], v[16:17], off
	s_nop 0
	v_addc_co_u32_e32 v53, vcc, 0, v53, vcc
	global_load_dwordx4 v[52:55], v[52:53], off
	s_mov_b32 s4, 0xf823c000
	v_add_u32_e32 v40, s20, v40
	v_lshl_add_u64 v[26:27], v[26:27], 0, s[20:21]
	s_waitcnt vmcnt(5)
	v_and_b32_e32 v39, 0xffff0000, v56
	s_waitcnt vmcnt(4)
	v_and_b32_e32 v85, 0xffff0000, v64
	v_lshlrev_b32_e32 v38, 16, v56
	v_lshlrev_b32_e32 v84, 16, v64
	v_mov_b32_e32 v66, v39
	v_mov_b32_e32 v67, v85
	v_lshlrev_b32_e32 v82, 16, v57
	v_and_b32_e32 v87, 0xffff0000, v65
	v_lshlrev_b32_e32 v86, 16, v65
	v_mov_b32_e32 v64, v38
	v_mov_b32_e32 v65, v84
	v_pk_mul_f32 v[66:67], v[66:67], v[66:67]
	v_and_b32_e32 v83, 0xffff0000, v57
	global_load_dwordx4 v[56:59], v[16:17], off offset:1024
	global_load_dwordx4 v[60:63], v[76:77], off offset:1024
	v_pk_fma_f32 v[64:65], v[64:65], v[64:65], v[66:67]
	v_mov_b32_e32 v66, v82
	v_mov_b32_e32 v67, v86
	v_mov_b32_e32 v68, v83
	v_mov_b32_e32 v69, v87
	v_pk_fma_f32 v[64:65], v[66:67], v[66:67], v[64:65]
	s_waitcnt vmcnt(5)
	v_and_b32_e32 v91, 0xffff0000, v72
	v_pk_fma_f32 v[88:89], v[68:69], v[68:69], v[64:65]
	global_load_dwordx4 v[64:67], v[16:17], off offset:2048
	global_load_dwordx4 v[68:71], v[76:77], off offset:2048
	v_lshlrev_b32_e32 v90, 16, v72
	v_and_b32_e32 v93, 0xffff0000, v73
	v_lshlrev_b32_e32 v92, 16, v73
	global_load_dwordx4 v[72:75], v[16:17], off offset:3072
	s_nop 0
	global_load_dwordx4 v[76:79], v[76:77], off offset:3072
	s_waitcnt vmcnt(8)
	v_and_b32_e32 v95, 0xffff0000, v80
	v_lshlrev_b32_e32 v94, 16, v80
	v_mov_b32_e32 v98, v91
	v_mov_b32_e32 v99, v95
	v_and_b32_e32 v97, 0xffff0000, v81
	v_lshlrev_b32_e32 v96, 16, v81
	v_mov_b32_e32 v80, v90
	v_mov_b32_e32 v81, v94
	v_pk_mul_f32 v[98:99], v[98:99], v[98:99]
	v_mov_b32_e32 v100, v93
	v_pk_fma_f32 v[80:81], v[80:81], v[80:81], v[98:99]
	v_mov_b32_e32 v98, v92
	v_mov_b32_e32 v99, v96
	v_mov_b32_e32 v101, v97
	v_pk_fma_f32 v[80:81], v[98:99], v[98:99], v[80:81]
	v_add_f32_e32 v33, v88, v89
	v_pk_fma_f32 v[80:81], v[100:101], v[100:101], v[80:81]
	s_nop 0
	v_add_f32_e32 v33, v33, v80
	v_add_f32_e32 v33, v33, v81
	s_nop 0
	s_nop 1
	v_add_f32_dpp v33, v33, v33 quad_perm:[1,0,3,2] row_mask:0xf bank_mask:0xf
	s_nop 1
	v_add_f32_dpp v33, v33, v33 quad_perm:[2,3,0,1] row_mask:0xf bank_mask:0xf
	s_nop 1
	v_add_f32_dpp v33, v33, v33 row_half_mirror row_mask:0xf bank_mask:0xf
	s_nop 1
	v_add_f32_dpp v33, v33, v33 row_mirror row_mask:0xf bank_mask:0xf
	s_nop 1
	v_mov_b32_e32 v35, v33
	s_nop 1
	v_permlane16_swap_b32_e32 v33, v35
	s_nop 1
	v_add_f32_e32 v33, v33, v35
	s_nop 1
	v_mov_b32_e32 v35, v33
	s_nop 1
	v_permlane32_swap_b32_e32 v33, v35
	s_nop 1
	v_add_f32_e32 v33, v33, v35
	s_nop 1
	v_fmamk_f32 v33, v33, 0x3a800000, v219
	v_cmp_gt_f32_e32 vcc, s25, v33
	v_mul_f32_e32 v35, 0x4b800000, v33
	s_nop 0
	v_cndmask_b32_e32 v33, v33, v35, vcc
	v_rsq_f32_e32 v33, v33
	s_nop 0
	v_mul_f32_e32 v35, 0x45800000, v33
	v_cndmask_b32_e32 v80, v33, v35, vcc
	v_pk_mul_f32 v[38:39], v[80:81], v[38:39] op_sel_hi:[0,1]
	s_waitcnt vmcnt(7)
	v_pk_mul_f32 v[38:39], v[48:49], v[38:39]
	v_pk_mul_f32 v[48:49], v[80:81], v[82:83] op_sel_hi:[0,1]
	v_pk_mul_f32 v[50:51], v[50:51], v[48:49]
	s_waitcnt vmcnt(6)
	v_pk_fma_f32 v[48:49], v[52:53], v[38:39], v[12:13]
	v_pk_mul_f32 v[12:13], v[80:81], v[84:85] op_sel_hi:[0,1]
	v_pk_fma_f32 v[50:51], v[54:55], v[50:51], v[14:15]
	s_waitcnt vmcnt(5)
	v_pk_mul_f32 v[12:13], v[56:57], v[12:13]
	v_pk_mul_f32 v[14:15], v[80:81], v[86:87] op_sel_hi:[0,1]
	v_pk_mul_f32 v[14:15], v[58:59], v[14:15]
	s_waitcnt vmcnt(4)
	v_pk_fma_f32 v[8:9], v[60:61], v[12:13], v[8:9]
	v_pk_mul_f32 v[12:13], v[80:81], v[90:91] op_sel_hi:[0,1]
	v_pk_fma_f32 v[10:11], v[62:63], v[14:15], v[10:11]
	s_waitcnt vmcnt(3)
	v_pk_mul_f32 v[12:13], v[12:13], v[64:65]
	v_pk_mul_f32 v[14:15], v[80:81], v[92:93] op_sel_hi:[0,1]
	v_pk_mul_f32 v[14:15], v[14:15], v[66:67]
	s_waitcnt vmcnt(2)
	v_pk_fma_f32 v[4:5], v[12:13], v[68:69], v[4:5]
	v_pk_mul_f32 v[12:13], v[80:81], v[94:95] op_sel_hi:[0,1]
	v_pk_fma_f32 v[6:7], v[14:15], v[70:71], v[6:7]
	s_waitcnt vmcnt(1)
	v_pk_mul_f32 v[12:13], v[12:13], v[72:73]
	v_pk_mul_f32 v[14:15], v[80:81], v[96:97] op_sel_hi:[0,1]
	v_pk_mul_f32 v[14:15], v[14:15], v[74:75]
	s_waitcnt vmcnt(0)
	v_pk_fma_f32 v[0:1], v[12:13], v[76:77], v[0:1]
	v_add_u32_e32 v12, 3, v31
	v_pk_fma_f32 v[2:3], v[14:15], v[78:79], v[2:3]
	global_store_dwordx4 v[36:37], v[48:51], off nt
	global_store_dwordx4 v[36:37], v[8:11], off offset:1024 nt
	global_store_dwordx4 v[36:37], v[4:7], off offset:2048 nt
	global_store_dwordx4 v[36:37], v[0:3], off offset:3072 nt
	v_mul_hi_i32_i24_e32 v41, 0x6000, v12
	v_mul_i32_i24_e32 v42, 0x6000, v12
	v_mov_b32_e32 v44, v42
	v_mov_b32_e32 v45, v41
	v_lshl_add_u64 v[46:47], s[96:97], 0, v[44:45]
	v_lshl_add_u64 v[44:45], v[46:47], 0, s[28:29]
	v_lshl_add_u64 v[68:69], v[44:45], 0, v[192:193]
	v_lshl_add_u64 v[70:71], v[46:47], 0, v[192:193]
	global_load_dwordx4 v[72:75], v[18:19], off
	global_load_dwordx4 v[76:79], v[68:69], off
	global_load_dwordx4 v[84:87], v[70:71], off
	v_mov_b32_e32 v43, v193
	v_mov_b32_e32 v46, v30
	v_mov_b32_e32 v47, v43
	v_lshl_add_u64 v[88:89], v[44:45], 0, v[46:47]
	global_load_dwordx4 v[92:95], v[20:21], off
	global_load_dwordx4 v[96:99], v[88:89], off
	global_load_dwordx4 v[106:109], v[70:71], off offset:1024
	v_mov_b32_e32 v46, v193
	v_mov_b32_e32 v47, v193
	v_mov_b32_e32 v68, v32
	v_mov_b32_e32 v69, v46
	v_lshl_add_u64 v[100:101], v[44:45], 0, v[68:69]
	global_load_dwordx4 v[116:119], v[22:23], off
	global_load_dwordx4 v[120:123], v[100:101], off
	global_load_dwordx4 v[124:127], v[70:71], off offset:2048
	v_mov_b32_e32 v68, v34
	v_mov_b32_e32 v69, v47
	v_lshl_add_u64 v[110:111], v[44:45], 0, v[68:69]
	global_load_dwordx4 v[136:139], v[24:25], off
	global_load_dwordx4 v[140:143], v[110:111], off
	global_load_dwordx4 v[144:147], v[70:71], off offset:3072
	v_mul_hi_i32_i24_e32 v13, 0x6000, v12
	v_mul_i32_i24_e32 v12, 0x6000, v12
	v_mov_b32_e32 v36, v49
	v_mov_b32_e32 v37, v9
	v_lshl_add_u64 v[14:15], s[96:97], 0, v[12:13]
	v_mov_b32_e32 v12, v48
	v_mov_b32_e32 v13, v8
	v_pk_mul_f32 v[36:37], v[36:37], v[36:37]
	v_mov_b32_e32 v38, v5
	v_pk_fma_f32 v[12:13], v[12:13], v[12:13], v[36:37]
	v_mov_b32_e32 v36, v50
	v_mov_b32_e32 v37, v10
	v_pk_fma_f32 v[12:13], v[36:37], v[36:37], v[12:13]
	v_mov_b32_e32 v36, v51
	v_mov_b32_e32 v37, v11
	v_mov_b32_e32 v39, v1
	v_pk_fma_f32 v[12:13], v[36:37], v[36:37], v[12:13]
	v_mov_b32_e32 v36, v4
	v_mov_b32_e32 v37, v0
	v_pk_mul_f32 v[38:39], v[38:39], v[38:39]
	v_add_f32_e32 v12, v12, v13
	v_pk_fma_f32 v[36:37], v[36:37], v[36:37], v[38:39]
	v_mov_b32_e32 v38, v6
	v_mov_b32_e32 v39, v2
	v_pk_fma_f32 v[36:37], v[38:39], v[38:39], v[36:37]
	v_mov_b32_e32 v38, v7
	v_mov_b32_e32 v39, v3
	v_pk_fma_f32 v[36:37], v[38:39], v[38:39], v[36:37]
	s_nop 0
	v_add_f32_e32 v12, v12, v36
	v_add_f32_e32 v12, v12, v37
	v_lshl_add_u64 v[36:37], v[14:15], 0, s[28:29]
	v_lshl_add_u64 v[38:39], v[36:37], 0, v[192:193]
	v_lshl_add_u64 v[14:15], v[14:15], 0, v[192:193]
	v_mov_b32_e32 v38, v48
	v_mov_b32_e32 v39, v50
	v_mov_b32_e32 v50, v49
	s_nop 0
	s_nop 1
	v_add_f32_dpp v12, v12, v12 quad_perm:[1,0,3,2] row_mask:0xf bank_mask:0xf
	s_nop 1
	v_add_f32_dpp v12, v12, v12 quad_perm:[2,3,0,1] row_mask:0xf bank_mask:0xf
	s_nop 1
	v_add_f32_dpp v12, v12, v12 row_half_mirror row_mask:0xf bank_mask:0xf
	s_nop 1
	v_add_f32_dpp v12, v12, v12 row_mirror row_mask:0xf bank_mask:0xf
	s_nop 1
	v_mov_b32_e32 v13, v12
	s_nop 1
	v_permlane16_swap_b32_e32 v12, v13
	s_nop 1
	v_add_f32_e32 v12, v12, v13
	s_nop 1
	v_mov_b32_e32 v13, v12
	s_nop 1
	v_permlane32_swap_b32_e32 v12, v13
	s_nop 1
	v_add_f32_e32 v12, v12, v13
	s_nop 1
	v_fmamk_f32 v12, v12, 0x3a800000, v219
	v_cmp_gt_f32_e32 vcc, s25, v12
	v_mul_f32_e32 v13, 0x4b800000, v12
	s_waitcnt vmcnt(11)
	v_mov_b32_e32 v52, v72
	v_mov_b32_e32 v53, v73
	v_mov_b32_e32 v54, v74
	v_mov_b32_e32 v55, v75
	v_mov_b32_e32 v64, v52
	v_cndmask_b32_e32 v12, v12, v13, vcc
	v_rsq_f32_e32 v12, v12
	v_mov_b32_e32 v65, v54
	v_mov_b32_e32 v54, v53
	s_waitcnt vmcnt(9)
	v_mov_b32_e32 v56, v76
	v_mov_b32_e32 v57, v77
	v_mov_b32_e32 v58, v78
	v_mov_b32_e32 v59, v79
	v_mov_b32_e32 v60, v84
	v_mov_b32_e32 v61, v85
	v_mov_b32_e32 v62, v86
	v_mov_b32_e32 v63, v87
	v_mov_b32_e32 v67, v62
	v_mul_f32_e32 v13, 0x45800000, v12
	v_cndmask_b32_e32 v12, v12, v13, vcc
	v_pk_mul_f32 v[38:39], v[38:39], v[12:13] op_sel_hi:[1,0]
	v_pk_mul_f32 v[48:49], v[50:51], v[12:13] op_sel_hi:[1,0]
	v_pk_mul_f32 v[38:39], v[64:65], v[38:39]
	v_mov_b32_e32 v65, v58
	v_mov_b32_e32 v58, v57
	v_mov_b32_e32 v64, v56
	v_pk_mul_f32 v[48:49], v[54:55], v[48:49]
	v_pk_add_f32 v[50:51], v[58:59], 1.0 op_sel_hi:[1,0]
	v_mov_b32_e32 v62, v61
	v_pk_add_f32 v[64:65], v[64:65], 1.0 op_sel_hi:[1,0]
	v_mov_b32_e32 v66, v60
	v_pk_fma_f32 v[48:49], v[50:51], v[48:49], v[62:63]
	v_pk_fma_f32 v[38:39], v[64:65], v[38:39], v[66:67]
	v_and_b32_sdwa v33, v49, v218 dst_sel:DWORD dst_unused:UNUSED_PAD src0_sel:WORD_1 src1_sel:DWORD
	v_and_b32_sdwa v13, v39, v218 dst_sel:DWORD dst_unused:UNUSED_PAD src0_sel:WORD_1 src1_sel:DWORD
	v_cvt_pk_bf16_f32 v38, v38, v48
	v_add3_u32 v33, v49, v33, s80
	v_add3_u32 v13, v39, v13, s80
	v_and_b32_e32 v33, 0xffff0000, v33
	v_add_co_u32_e32 v48, vcc, s4, v28
	v_or_b32_sdwa v39, v33, v13 dst_sel:DWORD dst_unused:UNUSED_PAD src0_sel:DWORD src1_sel:WORD_1
	s_nop 0
	v_addc_co_u32_e32 v49, vcc, -1, v29, vcc
	global_store_dwordx2 v[48:49], v[38:39], off
	v_mov_b32_e32 v31, v193
	v_lshl_add_u64 v[38:39], v[36:37], 0, v[30:31]
	v_mov_b32_e32 v38, v8
	v_mov_b32_e32 v39, v10
	v_pk_mul_f32 v[38:39], v[38:39], v[12:13] op_sel_hi:[1,0]
	v_mov_b32_e32 v10, v9
	v_pk_mul_f32 v[8:9], v[10:11], v[12:13] op_sel_hi:[1,0]
	s_mov_b32 s4, 0xf823d000
	v_mov_b32_e32 v33, v193
	v_mov_b32_e32 v35, v193
	s_waitcnt vmcnt(9)
	v_mov_b32_e32 v48, v92
	v_mov_b32_e32 v49, v93
	v_mov_b32_e32 v50, v94
	v_mov_b32_e32 v51, v95
	v_mov_b32_e32 v60, v48
	v_mov_b32_e32 v61, v50
	v_pk_mul_f32 v[38:39], v[38:39], v[60:61]
	s_waitcnt vmcnt(8)
	v_mov_b32_e32 v52, v96
	v_mov_b32_e32 v53, v97
	v_mov_b32_e32 v54, v98
	v_mov_b32_e32 v55, v99
	v_mov_b32_e32 v60, v52
	v_mov_b32_e32 v61, v54
	v_pk_add_f32 v[60:61], v[60:61], 1.0 op_sel_hi:[1,0]
	s_waitcnt vmcnt(7)
	v_mov_b32_e32 v56, v106
	v_mov_b32_e32 v57, v107
	v_mov_b32_e32 v58, v108
	v_mov_b32_e32 v59, v109
	v_mov_b32_e32 v62, v56
	v_mov_b32_e32 v63, v58
	v_mov_b32_e32 v50, v49
	v_mov_b32_e32 v54, v53
	v_pk_fma_f32 v[38:39], v[38:39], v[60:61], v[62:63]
	v_pk_mul_f32 v[8:9], v[8:9], v[50:51]
	v_pk_add_f32 v[10:11], v[54:55], 1.0 op_sel_hi:[1,0]
	v_mov_b32_e32 v58, v57
	v_pk_fma_f32 v[8:9], v[8:9], v[10:11], v[58:59]
	v_and_b32_sdwa v11, v38, v218 dst_sel:DWORD dst_unused:UNUSED_PAD src0_sel:WORD_1 src1_sel:DWORD
	v_add3_u32 v13, v38, v11, s80
	v_and_b32_sdwa v31, v8, v218 dst_sel:DWORD dst_unused:UNUSED_PAD src0_sel:WORD_1 src1_sel:DWORD
	v_cvt_pk_bf16_f32 v11, v39, v9
	v_add3_u32 v8, v8, v31, s80
	v_and_b32_e32 v8, 0xffff0000, v8
	v_or_b32_sdwa v10, v8, v13 dst_sel:DWORD dst_unused:UNUSED_PAD src0_sel:DWORD src1_sel:WORD_1
	v_add_co_u32_e32 v8, vcc, s4, v28
	s_nop 1
	v_addc_co_u32_e32 v9, vcc, -1, v29, vcc
	global_store_dwordx2 v[8:9], v[10:11], off offset:-3584
	v_lshl_add_u64 v[10:11], v[36:37], 0, v[32:33]
	v_mov_b32_e32 v10, v4
	v_mov_b32_e32 v11, v6
	v_pk_mul_f32 v[10:11], v[10:11], v[12:13] op_sel_hi:[1,0]
	v_mov_b32_e32 v6, v5
	v_pk_mul_f32 v[4:5], v[6:7], v[12:13] op_sel_hi:[1,0]
	v_cmp_lt_i32_e32 vcc, s26, v40
	v_lshl_add_u64 v[28:29], v[28:29], 0, s[30:31]
	s_or_b64 s[2:3], vcc, s[2:3]
	s_waitcnt vmcnt(7)
	v_mov_b32_e32 v48, v116
	v_mov_b32_e32 v49, v117
	v_mov_b32_e32 v50, v118
	v_mov_b32_e32 v51, v119
	v_mov_b32_e32 v38, v48
	v_mov_b32_e32 v39, v50
	v_pk_mul_f32 v[10:11], v[10:11], v[38:39]
	s_waitcnt vmcnt(6)
	v_mov_b32_e32 v52, v120
	v_mov_b32_e32 v53, v121
	v_mov_b32_e32 v54, v122
	v_mov_b32_e32 v55, v123
	v_mov_b32_e32 v38, v52
	v_mov_b32_e32 v39, v54
	v_pk_add_f32 v[38:39], v[38:39], 1.0 op_sel_hi:[1,0]
	s_waitcnt vmcnt(5)
	v_mov_b32_e32 v56, v124
	v_mov_b32_e32 v57, v125
	v_mov_b32_e32 v58, v126
	v_mov_b32_e32 v59, v127
	v_mov_b32_e32 v60, v56
	v_mov_b32_e32 v61, v58
	v_mov_b32_e32 v50, v49
	v_mov_b32_e32 v54, v53
	v_pk_fma_f32 v[10:11], v[10:11], v[38:39], v[60:61]
	v_pk_mul_f32 v[4:5], v[4:5], v[50:51]
	v_pk_add_f32 v[6:7], v[54:55], 1.0 op_sel_hi:[1,0]
	v_mov_b32_e32 v58, v57
	v_pk_fma_f32 v[4:5], v[4:5], v[6:7], v[58:59]
	v_cvt_pk_bf16_f32 v4, v10, v4
	v_cvt_pk_bf16_f32 v5, v11, v5
	global_store_dwordx2 v[8:9], v[4:5], off offset:-3072
	v_lshl_add_u64 v[10:11], v[36:37], 0, v[34:35]
	v_mov_b32_e32 v10, v0
	v_mov_b32_e32 v11, v2
	v_pk_mul_f32 v[10:11], v[10:11], v[12:13] op_sel_hi:[1,0]
	v_mov_b32_e32 v2, v1
	v_pk_mul_f32 v[0:1], v[2:3], v[12:13] op_sel_hi:[1,0]
	s_waitcnt vmcnt(5)
	v_mov_b32_e32 v4, v136
	v_mov_b32_e32 v5, v137
	v_mov_b32_e32 v6, v138
	v_mov_b32_e32 v7, v139
	v_mov_b32_e32 v14, v4
	v_mov_b32_e32 v15, v6
	v_pk_mul_f32 v[10:11], v[10:11], v[14:15]
	s_waitcnt vmcnt(4)
	v_mov_b32_e32 v36, v140
	v_mov_b32_e32 v37, v141
	v_mov_b32_e32 v38, v142
	v_mov_b32_e32 v39, v143
	v_mov_b32_e32 v15, v38
	v_mov_b32_e32 v6, v5
	v_mov_b32_e32 v38, v37
	v_mov_b32_e32 v14, v36
	s_waitcnt vmcnt(3)
	v_mov_b32_e32 v48, v144
	v_mov_b32_e32 v49, v145
	v_mov_b32_e32 v50, v146
	v_mov_b32_e32 v51, v147
	v_mov_b32_e32 v53, v50
	v_pk_mul_f32 v[0:1], v[0:1], v[6:7]
	v_pk_add_f32 v[2:3], v[38:39], 1.0 op_sel_hi:[1,0]
	v_mov_b32_e32 v50, v49
	v_pk_add_f32 v[14:15], v[14:15], 1.0 op_sel_hi:[1,0]
	v_mov_b32_e32 v52, v48
	v_pk_fma_f32 v[0:1], v[0:1], v[2:3], v[50:51]
	v_pk_fma_f32 v[10:11], v[10:11], v[14:15], v[52:53]
	v_cvt_pk_bf16_f32 v1, v11, v1
	v_cvt_pk_bf16_f32 v0, v10, v0
	global_store_dwordx2 v[8:9], v[0:1], off offset:-2560
	s_andn2_b64 exec, exec, s[2:3]
	s_cbranch_execnz .LBB0_34

.LBB0_80:
	s_andn2_b64 vcc, exec, s[0:1]
	s_cbranch_vccnz .LBB0_94
	s_add_i32 s78, s8, 0xfffffa6e
	s_and_b32 s0, s78, 0xffff
	s_mulk_i32 s0, 0x411
	s_lshr_b32 s0, s0, 16
	s_sub_i32 s1, s78, s0
	s_bfe_u32 s1, s1, 0xf0001
	s_add_i32 s1, s1, s0
	s_bfe_u32 s0, s1, 0xb0005
	s_lshl_b32 s1, s0, 12
	v_lshlrev_b32_e32 v2, 2, v32
	s_add_i32 s4, s1, 0x30000
	v_ashrrev_i32_e32 v3, 31, v2
	s_add_u32 s2, s60, s4
	s_addc_u32 s3, s61, 0
	v_lshlrev_b64 v[6:7], 2, v[2:3]
	v_lshl_add_u64 v[8:9], s[2:3], 0, v[6:7]
	global_load_dwordx4 v[14:17], v[8:9], off
	s_add_u32 s2, s62, s4
	s_addc_u32 s3, s63, 0
	s_add_i32 s1, s1, 0x48000
	v_lshl_add_u64 v[10:11], s[2:3], 0, v[6:7]
	global_load_dwordx4 v[18:21], v[10:11], off
	s_add_u32 s2, s60, s1
	s_addc_u32 s3, s61, 0
	v_lshl_add_u64 v[12:13], s[2:3], 0, v[6:7]
	global_load_dwordx4 v[22:25], v[12:13], off
	s_add_u32 s2, s62, s1
	s_addc_u32 s3, s63, 0
	v_lshl_add_u64 v[2:3], s[2:3], 0, v[6:7]
	global_load_dwordx4 v[2:5], v[2:3], off
	v_lshlrev_b32_e32 v1, 4, v32
	v_and_b32_e32 v192, 63, v32
	s_movk_i32 s1, 0x7f
	v_cmp_lt_i32_e32 vcc, s1, v32
	s_waitcnt vmcnt(3)
	ds_write_b128 v1, v[14:17] offset:17408
	s_waitcnt vmcnt(2)
	ds_write_b128 v1, v[18:21] offset:21504
	s_waitcnt vmcnt(1)
	ds_write_b128 v1, v[22:25] offset:25600
	s_waitcnt vmcnt(0)
	ds_write_b128 v1, v[2:5] offset:29696
	v_lshlrev_b32_e32 v3, 3, v32
	s_and_saveexec_b64 s[2:3], vcc
	s_xor_b64 s[2:3], exec, s[2:3]
	s_add_i32 s1, s0, 48
	v_and_b32_e32 v192, 63, v32
	v_lshlrev_b32_e32 v3, 3, v32
	v_mov_b32_e32 v4, s1
	s_or_saveexec_b64 s[2:3], s[2:3]
	s_mul_i32 s1, s0, 63
	s_sub_i32 s1, s78, s1
	s_and_b32 s5, s1, 0xffff
	s_sub_i32 s4, s5, 31
	s_xor_b64 exec, exec, s[2:3]
	s_cbranch_execz .LBB0_85
	s_sub_i32 s1, 31, s5
	v_ashrrev_i32_e32 v0, 6, v32
	s_cmp_lt_u32 s5, 31
	v_mul_lo_u32 v6, v0, 24
	s_cselect_b32 s7, s1, s4
	s_add_i32 s6, s0, 48
	v_ashrrev_i32_e32 v7, 31, v6
	s_mov_b32 s1, s79
	v_add_u32_e32 v0, s6, v6
	v_lshl_add_u64 v[6:7], s[0:1], 0, v[6:7]
	v_lshl_add_u64 v[6:7], v[6:7], 2, s[58:59]
	v_lshl_or_b32 v4, v0, 6, v192
	global_load_dword v0, v[6:7], off offset:192
	v_ashrrev_i32_e32 v5, 31, v4
	v_lshlrev_b64 v[8:9], 2, v[4:5]
	v_lshl_add_u64 v[4:5], s[54:55], 0, v[8:9]
	global_load_dword v4, v[4:5], off
	v_lshl_add_u64 v[8:9], s[56:57], 0, v[8:9]
	global_load_dword v5, v[8:9], off
	s_mov_b32 s1, 0x3fb8aa3b
	s_mov_b32 s9, 0xc2ce8ed0
	s_mov_b32 s12, 0x42b17218
	s_mov_b32 s10, 0x6dc9c883
	s_mov_b32 s11, 0x3fc45f30
	s_waitcnt vmcnt(2)
	v_mul_f32_e32 v2, 0x3fb8aa3b, v0
	v_fma_f32 v6, v0, s1, -v2
	v_rndne_f32_e32 v7, v2
	v_fmac_f32_e32 v6, 0x32a5705f, v0
	v_sub_f32_e32 v2, v2, v7
	v_add_f32_e32 v2, v2, v6
	v_exp_f32_e32 v2, v2
	v_cvt_i32_f32_e32 v6, v7
	v_cmp_ngt_f32_e32 vcc, s9, v0
	s_waitcnt vmcnt(0)
	v_cvt_f64_f32_e32 v[8:9], v5
	v_ldexp_f32 v2, v2, v6
	v_cndmask_b32_e32 v2, 0, v2, vcc
	v_cmp_nlt_f32_e32 vcc, s12, v0
	v_cvt_f32_i32_e32 v0, s7
	v_mul_f32_e32 v0, v4, v0
	v_cndmask_b32_e32 v14, v228, v2, vcc
	v_mul_f32_e32 v0, v0, v14
	v_mul_f32_e32 v2, 0x3fb8aa3b, v0
	v_fma_f32 v6, v0, s1, -v2
	v_rndne_f32_e32 v7, v2
	v_fmac_f32_e32 v6, 0x32a5705f, v0
	v_sub_f32_e32 v2, v2, v7
	v_add_f32_e32 v2, v2, v6
	v_exp_f32_e32 v2, v2
	v_cvt_i32_f32_e32 v6, v7
	v_cvt_f64_f32_e32 v[10:11], v14
	v_cmp_ngt_f32_e32 vcc, s9, v0
	v_ldexp_f32 v2, v2, v6
	v_cvt_f64_i32_e32 v[6:7], s7
	v_mul_f64 v[6:7], v[6:7], v[8:9]
	v_mul_f64 v[6:7], v[6:7], v[10:11]
	v_mul_f64 v[12:13], v[6:7], s[10:11]
	v_rndne_f64_e32 v[12:13], v[12:13]
	v_fma_f64 v[6:7], v[6:7], s[10:11], -v[12:13]
	v_cvt_f32_f64_e32 v6, v[6:7]
	v_cndmask_b32_e32 v2, 0, v2, vcc
	v_cmp_nlt_f32_e32 vcc, s12, v0
	v_cos_f32_e32 v0, v6
	v_sin_f32_e32 v6, v6
	v_cndmask_b32_e32 v2, v228, v2, vcc
	v_mul_f32_e32 v0, v2, v0
	v_mul_f32_e32 v2, v2, v6
	v_mul_f32_e32 v6, v4, v14
	v_mul_f32_e32 v7, 0x3fb8aa3b, v6
	v_fma_f32 v12, v6, s1, -v7
	v_rndne_f32_e32 v13, v7
	v_fmac_f32_e32 v12, 0x32a5705f, v6
	v_sub_f32_e32 v7, v7, v13
	v_add_f32_e32 v7, v7, v12
	v_exp_f32_e32 v7, v7
	v_cvt_i32_f32_e32 v12, v13
	v_cmp_ngt_f32_e32 vcc, s9, v6
	v_sub_u32_e32 v14, v1, v3
	v_ldexp_f32 v7, v7, v12
	v_cndmask_b32_e32 v7, 0, v7, vcc
	v_cmp_nlt_f32_e32 vcc, s12, v6
	s_nop 1
	v_cndmask_b32_e32 v12, v228, v7, vcc
	v_mul_f64 v[6:7], v[8:9], v[10:11]
	v_mul_f64 v[8:9], v[6:7], s[10:11]
	v_rndne_f64_e32 v[8:9], v[8:9]
	v_fma_f64 v[6:7], v[6:7], s[10:11], -v[8:9]
	v_cvt_f32_f64_e32 v6, v[6:7]
	v_cos_f32_e32 v7, v6
	v_sin_f32_e32 v6, v6
	v_mov_b32_e32 v10, v5
	v_fma_f32 v8, v12, v7, -1.0
	v_mul_f32_e32 v9, v12, v6
	v_pk_mul_f32 v[6:7], v[4:5], v[4:5]
	v_pk_mul_f32 v[12:13], v[10:11], v[8:9] op_sel:[0,1] op_sel_hi:[0,0]
	v_pk_fma_f32 v[10:11], v[4:5], v[8:9], v[12:13]
	v_pk_fma_f32 v[8:9], v[4:5], v[8:9], v[12:13] op_sel_hi:[0,1,1] neg_lo:[0,0,1] neg_hi:[0,0,1]
	v_pk_add_f32 v[4:5], v[6:7], v[6:7] op_sel:[0,1] op_sel_hi:[0,1]
	v_rcp_f32_e32 v6, v5
	s_nop 0
	v_mul_f32_e32 v5, v9, v6
	v_div_scale_f32 v1, s[10:11], v4, v4, v10
	v_rcp_f32_e32 v6, v1
	s_nop 0
	v_fma_f32 v7, -v1, v6, 1.0
	v_fmac_f32_e32 v6, v7, v6
	v_div_scale_f32 v7, vcc, v10, v4, v10
	v_mul_f32_e32 v8, v7, v6
	v_fma_f32 v9, -v1, v8, v7
	v_fmac_f32_e32 v8, v9, v6
	v_fma_f32 v1, -v1, v8, v7
	v_div_fmas_f32 v1, v1, v6, v8
	v_div_fixup_f32 v4, v1, v4, v10
	v_pk_mul_f32 v[6:7], v[2:3], v[4:5] op_sel:[0,1] op_sel_hi:[0,0]
	v_pk_fma_f32 v[8:9], v[0:1], v[4:5], v[6:7] neg_lo:[0,0,1] neg_hi:[0,0,1]
	v_pk_fma_f32 v[0:1], v[0:1], v[4:5], v[6:7] op_sel_hi:[0,1,1]
	v_mov_b32_e32 v9, v1
	v_mov_b32_e32 v4, s6
	ds_write_b64 v14, v[8:9]

.LBB0_182:
	v_min_i32_e32 v2, 0x4000, v16
	v_ashrrev_i32_e32 v2, 13, v2
	v_mov_b32_e32 v53, v193
	v_lshlrev_b64 v[60:61], 11, v[16:17]
	v_add_u32_e32 v2, s8, v2
	v_lshl_add_u64 v[0:1], v[0:1], 0, v[52:53]
	v_lshl_add_u64 v[16:17], v[44:45], 0, v[60:61]
	v_mul_hi_i32_i24_e32 v63, 0x6000, v2
	v_mul_i32_i24_e32 v62, 0x6000, v2
	global_load_dwordx4 v[12:15], v[0:1], off nt
	global_load_dwordx4 v[8:11], v[0:1], off offset:1024 nt
	global_load_dwordx4 v[4:7], v[0:1], off offset:2048 nt
	s_nop 0
	global_load_dwordx4 v[0:3], v[0:1], off offset:3072 nt
	s_nop 0
	global_load_dwordx2 v[24:25], v[16:17], off
	global_load_dwordx2 v[32:33], v[16:17], off offset:512
	global_load_dwordx2 v[40:41], v[16:17], off offset:1024
	global_load_dwordx2 v[76:77], v[16:17], off offset:1536
	v_lshl_add_u64 v[18:19], s[90:91], 0, v[62:63]
	v_lshl_add_u64 v[20:21], v[18:19], 0, v[52:53]
	s_mov_b64 s[0:1], 0x345a000
	v_lshl_add_u64 v[84:85], v[20:21], 0, s[0:1]
	s_mov_b32 s0, 0x345a000
	v_add_co_u32_e32 v20, vcc, s0, v20
	global_load_dwordx4 v[16:19], v[46:47], off
	s_nop 0
	v_addc_co_u32_e32 v21, vcc, 0, v21, vcc
	global_load_dwordx4 v[20:23], v[20:21], off
	s_mov_b32 s0, 0x800000
	s_mov_b64 s[10:11], 0x3000
	v_mov_b32_e32 v59, v193
	s_waitcnt vmcnt(5)
	v_and_b32_e32 v67, 0xffff0000, v24
	s_waitcnt vmcnt(4)
	v_and_b32_e32 v69, 0xffff0000, v32
	v_lshlrev_b32_e32 v66, 16, v24
	v_lshlrev_b32_e32 v68, 16, v32
	v_mov_b32_e32 v34, v67
	v_mov_b32_e32 v35, v69
	v_lshlrev_b32_e32 v70, 16, v25
	v_and_b32_e32 v73, 0xffff0000, v33
	v_lshlrev_b32_e32 v72, 16, v33
	v_mov_b32_e32 v32, v66
	v_mov_b32_e32 v33, v68
	v_pk_mul_f32 v[34:35], v[34:35], v[34:35]
	v_and_b32_e32 v71, 0xffff0000, v25
	global_load_dwordx4 v[28:31], v[46:47], off offset:1024
	global_load_dwordx4 v[24:27], v[84:85], off offset:1024
	v_pk_fma_f32 v[32:33], v[32:33], v[32:33], v[34:35]
	v_mov_b32_e32 v34, v70
	v_mov_b32_e32 v35, v72
	v_mov_b32_e32 v36, v71
	v_mov_b32_e32 v37, v73
	v_pk_fma_f32 v[32:33], v[34:35], v[34:35], v[32:33]
	s_waitcnt vmcnt(5)
	v_and_b32_e32 v75, 0xffff0000, v40
	v_pk_fma_f32 v[78:79], v[36:37], v[36:37], v[32:33]
	global_load_dwordx4 v[36:39], v[46:47], off offset:2048
	global_load_dwordx4 v[32:35], v[84:85], off offset:2048
	v_lshlrev_b32_e32 v74, 16, v40
	v_and_b32_e32 v83, 0xffff0000, v41
	v_lshlrev_b32_e32 v82, 16, v41
	global_load_dwordx4 v[40:43], v[46:47], off offset:3072
	global_load_dwordx4 v[92:95], v[84:85], off offset:3072
	s_waitcnt vmcnt(8)
	v_and_b32_e32 v81, 0xffff0000, v76
	v_lshlrev_b32_e32 v80, 16, v76
	v_mov_b32_e32 v96, v75
	v_mov_b32_e32 v97, v81
	v_and_b32_e32 v85, 0xffff0000, v77
	v_lshlrev_b32_e32 v84, 16, v77
	v_mov_b32_e32 v76, v74
	v_mov_b32_e32 v77, v80
	v_pk_mul_f32 v[96:97], v[96:97], v[96:97]
	v_mov_b32_e32 v98, v83
	v_pk_fma_f32 v[76:77], v[76:77], v[76:77], v[96:97]
	v_mov_b32_e32 v96, v82
	v_mov_b32_e32 v97, v84
	v_mov_b32_e32 v99, v85
	v_pk_fma_f32 v[76:77], v[96:97], v[96:97], v[76:77]
	v_add_f32_e32 v55, v78, v79
	v_pk_fma_f32 v[76:77], v[98:99], v[98:99], v[76:77]
	s_nop 0
	v_add_f32_e32 v55, v55, v76
	v_add_f32_e32 v55, v55, v77
	s_nop 0
	s_nop 1
	v_add_f32_dpp v55, v55, v55 quad_perm:[1,0,3,2] row_mask:0xf bank_mask:0xf
	s_nop 1
	v_add_f32_dpp v55, v55, v55 quad_perm:[2,3,0,1] row_mask:0xf bank_mask:0xf
	s_nop 1
	v_add_f32_dpp v55, v55, v55 row_half_mirror row_mask:0xf bank_mask:0xf
	s_nop 1
	v_add_f32_dpp v55, v55, v55 row_mirror row_mask:0xf bank_mask:0xf
	s_nop 1
	v_mov_b32_e32 v57, v55
	s_nop 1
	v_permlane16_swap_b32_e32 v55, v57
	s_nop 1
	v_add_f32_e32 v55, v55, v57
	s_nop 1
	v_mov_b32_e32 v57, v55
	s_nop 1
	v_permlane32_swap_b32_e32 v55, v57
	s_nop 1
	v_add_f32_e32 v55, v55, v57
	s_nop 1
	v_fmamk_f32 v55, v55, 0x3a800000, v219
	v_cmp_gt_f32_e32 vcc, s0, v55
	v_mul_f32_e32 v57, 0x4b800000, v55
	s_nop 0
	v_cndmask_b32_e32 v55, v55, v57, vcc
	v_rsq_f32_e32 v55, v55
	s_nop 0
	v_mul_f32_e32 v57, 0x45800000, v55
	v_cndmask_b32_e32 v76, v55, v57, vcc
	v_pk_mul_f32 v[66:67], v[76:77], v[66:67] op_sel_hi:[0,1]
	s_waitcnt vmcnt(7)
	v_pk_mul_f32 v[16:17], v[16:17], v[66:67]
	v_pk_mul_f32 v[66:67], v[76:77], v[70:71] op_sel_hi:[0,1]
	s_waitcnt vmcnt(6)
	v_pk_fma_f32 v[12:13], v[20:21], v[16:17], v[12:13]
	v_pk_mul_f32 v[16:17], v[76:77], v[68:69] op_sel_hi:[0,1]
	v_pk_mul_f32 v[18:19], v[18:19], v[66:67]
	s_waitcnt vmcnt(5)
	v_pk_mul_f32 v[16:17], v[28:29], v[16:17]
	v_pk_fma_f32 v[14:15], v[22:23], v[18:19], v[14:15]
	v_pk_mul_f32 v[18:19], v[76:77], v[72:73] op_sel_hi:[0,1]
	s_waitcnt vmcnt(4)
	v_pk_fma_f32 v[8:9], v[24:25], v[16:17], v[8:9]
	v_pk_mul_f32 v[16:17], v[76:77], v[74:75] op_sel_hi:[0,1]
	v_pk_mul_f32 v[18:19], v[30:31], v[18:19]
	s_waitcnt vmcnt(3)
	v_pk_mul_f32 v[16:17], v[16:17], v[36:37]
	v_pk_fma_f32 v[10:11], v[26:27], v[18:19], v[10:11]
	v_pk_mul_f32 v[18:19], v[76:77], v[82:83] op_sel_hi:[0,1]
	s_waitcnt vmcnt(2)
	v_pk_fma_f32 v[4:5], v[16:17], v[32:33], v[4:5]
	v_pk_mul_f32 v[16:17], v[76:77], v[80:81] op_sel_hi:[0,1]
	v_mov_b32_e32 v22, v13
	v_mov_b32_e32 v23, v9
	v_pk_mul_f32 v[18:19], v[18:19], v[38:39]
	s_waitcnt vmcnt(1)
	v_pk_mul_f32 v[16:17], v[16:17], v[40:41]
	v_mov_b32_e32 v20, v12
	v_mov_b32_e32 v21, v8
	v_pk_mul_f32 v[22:23], v[22:23], v[22:23]
	v_pk_fma_f32 v[6:7], v[18:19], v[34:35], v[6:7]
	v_pk_mul_f32 v[18:19], v[76:77], v[84:85] op_sel_hi:[0,1]
	s_waitcnt vmcnt(0)
	v_pk_fma_f32 v[0:1], v[16:17], v[92:93], v[0:1]
	v_pk_fma_f32 v[20:21], v[20:21], v[20:21], v[22:23]
	v_mov_b32_e32 v22, v14
	v_mov_b32_e32 v23, v10
	v_pk_mul_f32 v[18:19], v[18:19], v[42:43]
	v_pk_fma_f32 v[20:21], v[22:23], v[22:23], v[20:21]
	v_mov_b32_e32 v22, v15
	v_mov_b32_e32 v23, v11
	v_mov_b32_e32 v24, v5
	v_mov_b32_e32 v25, v1
	v_pk_fma_f32 v[2:3], v[18:19], v[94:95], v[2:3]
	v_pk_fma_f32 v[20:21], v[22:23], v[22:23], v[20:21]
	v_mov_b32_e32 v22, v4
	v_mov_b32_e32 v23, v0
	v_pk_mul_f32 v[24:25], v[24:25], v[24:25]
	v_lshl_add_u64 v[16:17], v[64:65], 0, v[52:53]
	v_pk_fma_f32 v[22:23], v[22:23], v[22:23], v[24:25]
	v_mov_b32_e32 v24, v6
	v_mov_b32_e32 v25, v2
	v_pk_fma_f32 v[22:23], v[24:25], v[24:25], v[22:23]
	v_mov_b32_e32 v24, v7
	v_mov_b32_e32 v25, v3
	v_pk_fma_f32 v[22:23], v[24:25], v[24:25], v[22:23]
	v_add_f32_e32 v20, v20, v21
	global_store_dwordx4 v[16:17], v[12:15], off nt
	global_store_dwordx4 v[16:17], v[8:11], off offset:1024 nt
	global_store_dwordx4 v[16:17], v[4:7], off offset:2048 nt
	global_store_dwordx4 v[16:17], v[0:3], off offset:3072 nt
	v_lshl_add_u64 v[40:41], s[96:97], 0, v[62:63]
	v_lshl_add_u64 v[42:43], v[40:41], 0, s[10:11]
	s_mov_b64 s[98:99], 0x4000
	v_lshl_add_u64 v[64:65], v[40:41], 0, s[98:99]
	v_lshl_add_u64 v[66:67], v[64:65], 0, v[52:53]
	v_lshl_add_u64 v[68:69], v[42:43], 0, v[52:53]
	global_load_dwordx4 v[70:73], v[48:49], off
	global_load_dwordx4 v[74:77], v[66:67], off
	global_load_dwordx4 v[92:95], v[68:69], off
	v_mov_b32_e32 v78, v193
	v_mov_b32_e32 v79, v193
	v_mov_b32_e32 v84, v54
	v_mov_b32_e32 v85, v78
	v_lshl_add_u64 v[96:97], v[42:43], 0, v[84:85]
	v_mov_b32_e32 v68, v54
	v_mov_b32_e32 v69, v78
	v_lshl_add_u64 v[84:85], v[64:65], 0, v[68:69]
	global_load_dwordx4 v[98:101], v[48:49], off offset:1024
	global_load_dwordx4 v[106:109], v[84:85], off
	global_load_dwordx4 v[116:119], v[96:97], off
	v_mov_b32_e32 v68, v56
	v_mov_b32_e32 v69, v79
	v_lshl_add_u64 v[110:111], v[42:43], 0, v[68:69]
	v_mov_b32_e32 v66, v56
	v_mov_b32_e32 v67, v79
	v_lshl_add_u64 v[68:69], v[64:65], 0, v[66:67]
	global_load_dwordx4 v[120:123], v[48:49], off offset:2048
	global_load_dwordx4 v[124:127], v[68:69], off
	global_load_dwordx4 v[136:139], v[110:111], off
	v_lshl_add_u64 v[66:67], v[64:65], 0, v[58:59]
	v_lshl_add_u64 v[84:85], v[42:43], 0, v[58:59]
	global_load_dwordx4 v[140:143], v[48:49], off offset:3072
	global_load_dwordx4 v[144:147], v[66:67], off
	global_load_dwordx4 v[148:151], v[84:85], off
	v_lshl_add_u64 v[16:17], s[96:97], 0, v[62:63]
	v_add_f32_e32 v20, v20, v22
	v_lshl_add_u64 v[18:19], v[16:17], 0, s[10:11]
	v_add_f32_e32 v22, v20, v23
	s_mov_b64 s[10:11], 0x4000
	s_mov_b64 s[98:99], 0x4000
	v_lshl_add_u64 v[20:21], v[16:17], 0, s[98:99]
	ds_bpermute_b32 v16, v86, v22
	v_lshl_add_u64 v[26:27], v[20:21], 0, v[52:53]
	v_lshl_add_u64 v[30:31], v[18:19], 0, v[52:53]
	v_mov_b32_e32 v34, v12
	v_mov_b32_e32 v35, v14
	s_waitcnt lgkmcnt(0)
	v_add_f32_e32 v16, v22, v16
	s_nop 0
	s_nop 0
	ds_bpermute_b32 v17, v87, v16
	v_mov_b32_e32 v14, v13
	v_mov_b32_e32 v55, v193
	v_mov_b32_e32 v57, v193
	s_waitcnt lgkmcnt(0)
	v_add_f32_e32 v16, v16, v17
	ds_bpermute_b32 v17, v88, v16
	s_waitcnt lgkmcnt(0)
	v_add_f32_e32 v16, v16, v17
	ds_bpermute_b32 v17, v89, v16
	s_waitcnt lgkmcnt(0)
	v_add_f32_e32 v16, v16, v17
	ds_bpermute_b32 v17, v90, v16
	s_waitcnt lgkmcnt(0)
	v_add_f32_e32 v16, v16, v17
	ds_bpermute_b32 v17, v91, v16
	s_waitcnt lgkmcnt(0)
	v_add_f32_e32 v16, v16, v17
	v_fmamk_f32 v16, v16, 0x3a800000, v219
	v_cmp_gt_f32_e32 vcc, s0, v16
	v_mul_f32_e32 v17, 0x4b800000, v16
	v_readlane_b32 s0, v255, 11
	v_cndmask_b32_e32 v16, v16, v17, vcc
	v_rsq_f32_e32 v16, v16
	v_add_u32_e32 v192, s0, v192
	s_movk_i32 s0, 0x1ff
	v_readlane_b32 s1, v255, 12
	v_mul_f32_e32 v17, 0x45800000, v16
	v_cndmask_b32_e32 v16, v16, v17, vcc
	v_pk_mul_f32 v[34:35], v[34:35], v[16:17] op_sel_hi:[1,0]
	v_pk_mul_f32 v[12:13], v[14:15], v[16:17] op_sel_hi:[1,0]
	v_cmp_lt_i32_e32 vcc, s0, v192
	s_or_b64 s[6:7], vcc, s[6:7]
	s_waitcnt vmcnt(11)
	v_mov_b32_e32 v22, v70
	v_mov_b32_e32 v23, v71
	v_mov_b32_e32 v24, v72
	v_mov_b32_e32 v25, v73
	v_mov_b32_e32 v36, v22
	v_mov_b32_e32 v37, v24
	v_pk_mul_f32 v[34:35], v[36:37], v[34:35]
	s_waitcnt vmcnt(10)
	v_mov_b32_e32 v26, v74
	v_mov_b32_e32 v27, v75
	v_mov_b32_e32 v28, v76
	v_mov_b32_e32 v29, v77
	v_mov_b32_e32 v36, v26
	v_mov_b32_e32 v37, v28
	v_pk_add_f32 v[36:37], v[36:37], 1.0 op_sel_hi:[1,0]
	s_waitcnt vmcnt(9)
	v_mov_b32_e32 v30, v92
	v_mov_b32_e32 v31, v93
	v_mov_b32_e32 v32, v94
	v_mov_b32_e32 v33, v95
	v_mov_b32_e32 v38, v30
	v_mov_b32_e32 v39, v32
	v_mov_b32_e32 v24, v23
	v_mov_b32_e32 v28, v27
	v_pk_fma_f32 v[34:35], v[36:37], v[34:35], v[38:39]
	v_pk_mul_f32 v[12:13], v[24:25], v[12:13]
	v_pk_add_f32 v[14:15], v[28:29], 1.0 op_sel_hi:[1,0]
	v_mov_b32_e32 v32, v31
	v_pk_fma_f32 v[12:13], v[14:15], v[12:13], v[32:33]
	v_and_b32_sdwa v15, v34, v218 dst_sel:DWORD dst_unused:UNUSED_PAD src0_sel:WORD_1 src1_sel:DWORD
	v_add3_u32 v17, v34, v15, s80
	v_and_b32_sdwa v22, v12, v218 dst_sel:DWORD dst_unused:UNUSED_PAD src0_sel:WORD_1 src1_sel:DWORD
	v_cvt_pk_bf16_f32 v15, v35, v13
	v_add3_u32 v12, v12, v22, s80
	v_and_b32_e32 v12, 0xffff0000, v12
	v_or_b32_sdwa v14, v12, v17 dst_sel:DWORD dst_unused:UNUSED_PAD src0_sel:DWORD src1_sel:WORD_1
	v_lshl_add_u64 v[12:13], v[50:51], 0, v[60:61]
	global_store_dwordx2 v[12:13], v[14:15], off
	v_lshl_add_u64 v[30:31], v[18:19], 0, v[54:55]
	v_lshl_add_u64 v[14:15], v[20:21], 0, v[54:55]
	s_nop 0
	v_mov_b32_e32 v14, v8
	v_mov_b32_e32 v15, v10
	v_pk_mul_f32 v[14:15], v[14:15], v[16:17] op_sel_hi:[1,0]
	v_mov_b32_e32 v10, v9
	v_pk_mul_f32 v[8:9], v[10:11], v[16:17] op_sel_hi:[1,0]
	s_waitcnt vmcnt(9)
	v_mov_b32_e32 v22, v98
	v_mov_b32_e32 v23, v99
	v_mov_b32_e32 v24, v100
	v_mov_b32_e32 v25, v101
	v_mov_b32_e32 v34, v22
	v_mov_b32_e32 v35, v24
	v_pk_mul_f32 v[14:15], v[14:15], v[34:35]
	s_waitcnt vmcnt(8)
	v_mov_b32_e32 v26, v106
	v_mov_b32_e32 v27, v107
	v_mov_b32_e32 v28, v108
	v_mov_b32_e32 v29, v109
	v_mov_b32_e32 v34, v26
	v_mov_b32_e32 v35, v28
	v_pk_add_f32 v[34:35], v[34:35], 1.0 op_sel_hi:[1,0]
	s_waitcnt vmcnt(7)
	v_mov_b32_e32 v30, v116
	v_mov_b32_e32 v31, v117
	v_mov_b32_e32 v32, v118
	v_mov_b32_e32 v33, v119
	v_mov_b32_e32 v36, v30
	v_mov_b32_e32 v37, v32
	v_mov_b32_e32 v24, v23
	v_mov_b32_e32 v28, v27
	v_pk_fma_f32 v[14:15], v[14:15], v[34:35], v[36:37]
	v_pk_mul_f32 v[8:9], v[8:9], v[24:25]
	v_pk_add_f32 v[10:11], v[28:29], 1.0 op_sel_hi:[1,0]
	v_mov_b32_e32 v32, v31
	v_pk_fma_f32 v[8:9], v[8:9], v[10:11], v[32:33]
	v_cvt_pk_bf16_f32 v8, v14, v8
	v_cvt_pk_bf16_f32 v9, v15, v9
	global_store_dwordx2 v[12:13], v[8:9], off offset:512
	v_lshl_add_u64 v[26:27], v[18:19], 0, v[56:57]
	v_lshl_add_u64 v[14:15], v[20:21], 0, v[56:57]
	s_nop 0
	v_mov_b32_e32 v14, v4
	v_mov_b32_e32 v15, v6
	v_pk_mul_f32 v[14:15], v[14:15], v[16:17] op_sel_hi:[1,0]
	v_mov_b32_e32 v6, v5
	v_pk_mul_f32 v[4:5], v[6:7], v[16:17] op_sel_hi:[1,0]
	s_waitcnt vmcnt(7)
	v_mov_b32_e32 v8, v120
	v_mov_b32_e32 v9, v121
	v_mov_b32_e32 v10, v122
	v_mov_b32_e32 v11, v123
	v_mov_b32_e32 v30, v8
	v_mov_b32_e32 v31, v10
	v_pk_mul_f32 v[14:15], v[14:15], v[30:31]
	s_waitcnt vmcnt(6)
	v_mov_b32_e32 v22, v124
	v_mov_b32_e32 v23, v125
	v_mov_b32_e32 v24, v126
	v_mov_b32_e32 v25, v127
	v_mov_b32_e32 v31, v24
	v_mov_b32_e32 v10, v9
	v_mov_b32_e32 v24, v23
	v_mov_b32_e32 v30, v22
	s_waitcnt vmcnt(5)
	v_mov_b32_e32 v26, v136
	v_mov_b32_e32 v27, v137
	v_mov_b32_e32 v28, v138
	v_mov_b32_e32 v29, v139
	v_mov_b32_e32 v33, v28
	v_pk_mul_f32 v[4:5], v[4:5], v[10:11]
	v_pk_add_f32 v[6:7], v[24:25], 1.0 op_sel_hi:[1,0]
	v_mov_b32_e32 v28, v27
	v_pk_add_f32 v[30:31], v[30:31], 1.0 op_sel_hi:[1,0]
	v_mov_b32_e32 v32, v26
	v_pk_fma_f32 v[4:5], v[4:5], v[6:7], v[28:29]
	v_pk_fma_f32 v[14:15], v[14:15], v[30:31], v[32:33]
	v_cvt_pk_bf16_f32 v5, v15, v5
	v_cvt_pk_bf16_f32 v4, v14, v4
	global_store_dwordx2 v[12:13], v[4:5], off offset:1024
	v_lshl_add_u64 v[8:9], v[20:21], 0, v[58:59]
	v_lshl_add_u64 v[14:15], v[18:19], 0, v[58:59]
	s_nop 0
	s_nop 0
	v_mov_b32_e32 v14, v0
	v_mov_b32_e32 v15, v2
	v_pk_mul_f32 v[14:15], v[14:15], v[16:17] op_sel_hi:[1,0]
	v_mov_b32_e32 v2, v1
	v_pk_mul_f32 v[0:1], v[2:3], v[16:17] op_sel_hi:[1,0]
	s_waitcnt vmcnt(5)
	v_mov_b32_e32 v4, v140
	v_mov_b32_e32 v5, v141
	v_mov_b32_e32 v6, v142
	v_mov_b32_e32 v7, v143
	v_mov_b32_e32 v22, v4
	v_mov_b32_e32 v23, v6
	v_pk_mul_f32 v[14:15], v[14:15], v[22:23]
	s_waitcnt vmcnt(4)
	v_mov_b32_e32 v8, v144
	v_mov_b32_e32 v9, v145
	v_mov_b32_e32 v10, v146
	v_mov_b32_e32 v11, v147
	v_mov_b32_e32 v23, v10
	v_mov_b32_e32 v6, v5
	v_mov_b32_e32 v10, v9
	v_mov_b32_e32 v22, v8
	s_waitcnt vmcnt(3)
	v_mov_b32_e32 v18, v148
	v_mov_b32_e32 v19, v149
	v_mov_b32_e32 v20, v150
	v_mov_b32_e32 v21, v151
	v_mov_b32_e32 v25, v20
	v_pk_mul_f32 v[0:1], v[0:1], v[6:7]
	v_pk_add_f32 v[2:3], v[10:11], 1.0 op_sel_hi:[1,0]
	v_mov_b32_e32 v20, v19
	v_pk_add_f32 v[22:23], v[22:23], 1.0 op_sel_hi:[1,0]
	v_mov_b32_e32 v24, v18
	v_pk_fma_f32 v[0:1], v[0:1], v[2:3], v[20:21]
	v_pk_fma_f32 v[14:15], v[14:15], v[22:23], v[24:25]
	v_cvt_pk_bf16_f32 v1, v15, v1
	v_cvt_pk_bf16_f32 v0, v14, v0
	global_store_dwordx2 v[12:13], v[0:1], off offset:1536
	s_andn2_b64 exec, exec, s[6:7]
	s_cbranch_execz .LBB0_188

.LBB0_1030:
	s_or_b64 exec, exec, s[4:5]
	v_lshl_add_u64 v[0:1], v[0:1], 0, v[192:193]
	global_load_dwordx4 v[36:39], v[0:1], off nt
	global_load_dwordx4 v[8:11], v[0:1], off offset:1024 nt
	global_load_dwordx4 v[4:7], v[0:1], off offset:2048 nt
	s_nop 0
	global_load_dwordx4 v[0:3], v[0:1], off offset:3072 nt
	s_nop 0
	global_load_dwordx4 v[40:43], v[14:15], off
	v_min_i32_e32 v13, 0x4000, v28
	v_ashrrev_i32_e32 v13, 13, v13
	v_mul_hi_i32_i24_e32 v25, 0x6000, v13
	v_mul_i32_i24_e32 v24, 0x6000, v13
	v_lshl_add_u64 v[26:27], s[96:97], 0, v[24:25]
	s_mov_b64 s[4:5], 0x1000
	v_lshl_add_u64 v[24:25], v[26:27], 0, v[192:193]
	v_lshl_add_u64 v[26:27], v[26:27], 0, s[4:5]
	v_lshl_add_u64 v[48:49], v[26:27], 0, v[192:193]
	global_load_dwordx4 v[44:47], v[24:25], off
	s_mov_b32 s4, 0x800000
	global_load_dwordx4 v[48:51], v[48:49], off
	v_mov_b32_e32 v68, v193
	global_load_dwordx4 v[70:73], v[14:15], off offset:1024
	v_mov_b32_e32 v74, v18
	v_mov_b32_e32 v75, v68
	v_lshl_add_u64 v[76:77], v[26:27], 0, v[74:75]
	global_load_dwordx4 v[84:87], v[76:77], off
	global_load_dwordx4 v[92:95], v[24:25], off offset:1024
	v_mov_b32_e32 v69, v193
	global_load_dwordx4 v[96:99], v[14:15], off offset:2048
	v_mov_b32_e32 v74, v20
	v_mov_b32_e32 v75, v69
	v_lshl_add_u64 v[78:79], v[26:27], 0, v[74:75]
	global_load_dwordx4 v[106:109], v[78:79], off
	global_load_dwordx4 v[116:119], v[24:25], off offset:2048
	v_mov_b32_e32 v74, v193
	global_load_dwordx4 v[120:123], v[14:15], off offset:3072
	v_mov_b32_e32 v88, v22
	v_mov_b32_e32 v89, v74
	v_lshl_add_u64 v[100:101], v[26:27], 0, v[88:89]
	global_load_dwordx4 v[124:127], v[100:101], off
	global_load_dwordx4 v[136:139], v[24:25], off offset:3072
	v_lshlrev_b64 v[28:29], 11, v[28:29]
	v_lshl_add_u64 v[28:29], v[16:17], 0, v[28:29]
	s_waitcnt vmcnt(15)
	v_mov_b32_e32 v54, v37
	s_waitcnt vmcnt(14)
	v_mov_b32_e32 v55, v9
	v_mov_b32_e32 v52, v36
	v_mov_b32_e32 v53, v8
	s_waitcnt vmcnt(13)
	v_mov_b32_e32 v62, v5
	s_waitcnt vmcnt(12)
	v_mov_b32_e32 v63, v1
	v_pk_mul_f32 v[54:55], v[54:55], v[54:55]
	v_mov_b32_e32 v56, v38
	v_mov_b32_e32 v57, v10
	v_mov_b32_e32 v60, v4
	v_mov_b32_e32 v61, v0
	v_pk_mul_f32 v[62:63], v[62:63], v[62:63]
	v_pk_fma_f32 v[52:53], v[52:53], v[52:53], v[54:55]
	v_mov_b32_e32 v58, v39
	v_mov_b32_e32 v59, v11
	v_mov_b32_e32 v64, v6
	v_mov_b32_e32 v65, v2
	v_pk_fma_f32 v[54:55], v[60:61], v[60:61], v[62:63]
	v_pk_fma_f32 v[52:53], v[56:57], v[56:57], v[52:53]
	v_mov_b32_e32 v66, v7
	v_mov_b32_e32 v67, v3
	v_pk_fma_f32 v[54:55], v[64:65], v[64:65], v[54:55]
	v_pk_fma_f32 v[52:53], v[58:59], v[58:59], v[52:53]
	v_pk_fma_f32 v[54:55], v[66:67], v[66:67], v[54:55]
	v_add_f32_e32 v13, v52, v53
	v_add_f32_e32 v13, v13, v54
	v_add_f32_e32 v13, v13, v55
	ds_bpermute_b32 v19, v30, v13
	s_waitcnt vmcnt(11)
	v_mov_b32_e32 v53, v42
	v_mov_b32_e32 v42, v41
	v_mov_b32_e32 v41, v38
	v_mov_b32_e32 v38, v37
	s_waitcnt lgkmcnt(0)
	v_add_f32_e32 v13, v13, v19
	ds_bpermute_b32 v19, v31, v13
	s_waitcnt vmcnt(10)
	v_mov_b32_e32 v37, v46
	v_mov_b32_e32 v46, v45
	s_waitcnt vmcnt(9)
	v_mov_b32_e32 v45, v50
	v_mov_b32_e32 v50, v49
	s_waitcnt lgkmcnt(0)
	v_add_f32_e32 v13, v13, v19
	ds_bpermute_b32 v21, v32, v13
	v_mov_b32_e32 v52, v40
	v_mov_b32_e32 v40, v36
	v_mov_b32_e32 v36, v44
	v_mov_b32_e32 v44, v48
	s_waitcnt lgkmcnt(0)
	v_add_f32_e32 v13, v13, v21
	ds_bpermute_b32 v21, v33, v13
	v_pk_add_f32 v[48:49], v[50:51], 1.0 op_sel_hi:[1,0]
	v_pk_add_f32 v[44:45], v[44:45], 1.0 op_sel_hi:[1,0]
	v_mov_b32_e32 v19, v193
	s_waitcnt lgkmcnt(0)
	v_add_f32_e32 v13, v13, v21
	ds_bpermute_b32 v21, v34, v13
	s_waitcnt lgkmcnt(0)
	v_add_f32_e32 v13, v13, v21
	ds_bpermute_b32 v21, v35, v13
	s_waitcnt lgkmcnt(0)
	v_add_f32_e32 v13, v13, v21
	v_fmamk_f32 v13, v13, 0x3a800000, v219
	v_mul_f32_e32 v21, 0x4b800000, v13
	v_cmp_gt_f32_e32 vcc, s4, v13
	v_readlane_b32 s4, v255, 11
	v_readlane_b32 s5, v255, 12
	v_cndmask_b32_e32 v13, v13, v21, vcc
	v_rsq_f32_e32 v13, v13
	v_add_u32_e32 v12, s4, v12
	s_movk_i32 s4, 0x1ff
	v_mul_f32_e32 v21, 0x45800000, v13
	v_cndmask_b32_e32 v50, v13, v21, vcc
	v_pk_mul_f32 v[40:41], v[40:41], v[50:51] op_sel_hi:[1,0]
	v_pk_mul_f32 v[38:39], v[38:39], v[50:51] op_sel_hi:[1,0]
	v_pk_mul_f32 v[40:41], v[52:53], v[40:41]
	v_pk_mul_f32 v[38:39], v[42:43], v[38:39]
	v_pk_fma_f32 v[36:37], v[44:45], v[40:41], v[36:37]
	v_pk_fma_f32 v[38:39], v[48:49], v[38:39], v[46:47]
	v_cvt_pk_bf16_f32 v36, v36, v38
	v_cvt_pk_bf16_f32 v37, v37, v39
	global_store_dwordx2 v[28:29], v[36:37], off
	v_lshl_add_u64 v[40:41], v[26:27], 0, v[18:19]
	s_nop 0
	v_mov_b32_e32 v48, v8
	v_mov_b32_e32 v49, v10
	v_mov_b32_e32 v10, v9
	v_pk_mul_f32 v[8:9], v[48:49], v[50:51] op_sel_hi:[1,0]
	v_pk_mul_f32 v[10:11], v[10:11], v[50:51] op_sel_hi:[1,0]
	v_mov_b32_e32 v21, v193
	v_cmp_lt_i32_e32 vcc, s4, v12
	s_or_b64 s[2:3], vcc, s[2:3]
	s_waitcnt vmcnt(9)
	v_mov_b32_e32 v36, v70
	v_mov_b32_e32 v37, v71
	v_mov_b32_e32 v38, v72
	v_mov_b32_e32 v39, v73
	v_mov_b32_e32 v49, v38
	s_waitcnt vmcnt(8)
	v_mov_b32_e32 v40, v84
	v_mov_b32_e32 v41, v85
	v_mov_b32_e32 v42, v86
	v_mov_b32_e32 v43, v87
	v_mov_b32_e32 v53, v42
	v_mov_b32_e32 v38, v37
	v_mov_b32_e32 v42, v41
	v_mov_b32_e32 v48, v36
	v_mov_b32_e32 v52, v40
	s_waitcnt vmcnt(7)
	v_mov_b32_e32 v44, v92
	v_mov_b32_e32 v45, v93
	v_mov_b32_e32 v46, v94
	v_mov_b32_e32 v47, v95
	v_mov_b32_e32 v55, v46
	v_mov_b32_e32 v46, v45
	v_pk_mul_f32 v[10:11], v[10:11], v[38:39]
	v_pk_add_f32 v[38:39], v[42:43], 1.0 op_sel_hi:[1,0]
	v_mov_b32_e32 v54, v44
	v_pk_mul_f32 v[8:9], v[8:9], v[48:49]
	v_pk_add_f32 v[36:37], v[52:53], 1.0 op_sel_hi:[1,0]
	v_pk_fma_f32 v[10:11], v[10:11], v[38:39], v[46:47]
	v_pk_fma_f32 v[8:9], v[8:9], v[36:37], v[54:55]
	v_cvt_pk_bf16_f32 v9, v9, v11
	v_cvt_pk_bf16_f32 v8, v8, v10
	global_store_dwordx2 v[28:29], v[8:9], off offset:512
	v_lshl_add_u64 v[36:37], v[26:27], 0, v[20:21]
	s_nop 0
	v_mov_b32_e32 v44, v4
	v_mov_b32_e32 v45, v6
	v_mov_b32_e32 v6, v5
	v_pk_mul_f32 v[4:5], v[44:45], v[50:51] op_sel_hi:[1,0]
	v_pk_mul_f32 v[6:7], v[6:7], v[50:51] op_sel_hi:[1,0]
	v_mov_b32_e32 v23, v193
	s_waitcnt vmcnt(7)
	v_mov_b32_e32 v8, v96
	v_mov_b32_e32 v9, v97
	v_mov_b32_e32 v10, v98
	v_mov_b32_e32 v11, v99
	v_mov_b32_e32 v45, v10
	s_waitcnt vmcnt(6)
	v_mov_b32_e32 v36, v106
	v_mov_b32_e32 v37, v107
	v_mov_b32_e32 v38, v108
	v_mov_b32_e32 v39, v109
	v_mov_b32_e32 v47, v38
	v_mov_b32_e32 v10, v9
	v_mov_b32_e32 v38, v37
	v_mov_b32_e32 v44, v8
	v_mov_b32_e32 v46, v36
	s_waitcnt vmcnt(5)
	v_mov_b32_e32 v40, v116
	v_mov_b32_e32 v41, v117
	v_mov_b32_e32 v42, v118
	v_mov_b32_e32 v43, v119
	v_mov_b32_e32 v49, v42
	v_mov_b32_e32 v42, v41
	v_pk_mul_f32 v[6:7], v[6:7], v[10:11]
	v_pk_add_f32 v[10:11], v[38:39], 1.0 op_sel_hi:[1,0]
	v_mov_b32_e32 v48, v40
	v_pk_mul_f32 v[4:5], v[4:5], v[44:45]
	v_pk_add_f32 v[8:9], v[46:47], 1.0 op_sel_hi:[1,0]
	v_pk_fma_f32 v[6:7], v[6:7], v[10:11], v[42:43]
	v_pk_fma_f32 v[4:5], v[4:5], v[8:9], v[48:49]
	v_cvt_pk_bf16_f32 v5, v5, v7
	v_cvt_pk_bf16_f32 v4, v4, v6
	global_store_dwordx2 v[28:29], v[4:5], off offset:1024
	v_lshl_add_u64 v[8:9], v[26:27], 0, v[22:23]
	s_nop 0
	v_mov_b32_e32 v36, v0
	v_mov_b32_e32 v37, v2
	v_mov_b32_e32 v2, v1
	v_pk_mul_f32 v[0:1], v[36:37], v[50:51] op_sel_hi:[1,0]
	v_pk_mul_f32 v[2:3], v[2:3], v[50:51] op_sel_hi:[1,0]
	s_waitcnt vmcnt(5)
	v_mov_b32_e32 v4, v120
	v_mov_b32_e32 v5, v121
	v_mov_b32_e32 v6, v122
	v_mov_b32_e32 v7, v123
	v_mov_b32_e32 v37, v6
	s_waitcnt vmcnt(4)
	v_mov_b32_e32 v8, v124
	v_mov_b32_e32 v9, v125
	v_mov_b32_e32 v10, v126
	v_mov_b32_e32 v11, v127
	v_mov_b32_e32 v39, v10
	v_mov_b32_e32 v6, v5
	v_mov_b32_e32 v10, v9
	v_mov_b32_e32 v36, v4
	v_mov_b32_e32 v38, v8
	s_waitcnt vmcnt(3)
	v_mov_b32_e32 v24, v136
	v_mov_b32_e32 v25, v137
	v_mov_b32_e32 v26, v138
	v_mov_b32_e32 v27, v139
	v_mov_b32_e32 v41, v26
	v_mov_b32_e32 v26, v25
	v_pk_mul_f32 v[2:3], v[2:3], v[6:7]
	v_pk_add_f32 v[6:7], v[10:11], 1.0 op_sel_hi:[1,0]
	v_mov_b32_e32 v40, v24
	v_pk_mul_f32 v[0:1], v[0:1], v[36:37]
	v_pk_add_f32 v[4:5], v[38:39], 1.0 op_sel_hi:[1,0]
	v_pk_fma_f32 v[2:3], v[2:3], v[6:7], v[26:27]
	v_pk_fma_f32 v[0:1], v[0:1], v[4:5], v[40:41]
	v_cvt_pk_bf16_f32 v1, v1, v3
	v_cvt_pk_bf16_f32 v0, v0, v2
	global_store_dwordx2 v[28:29], v[0:1], off offset:1536
	s_andn2_b64 exec, exec, s[2:3]
	s_cbranch_execz .LBB0_1035
